# hyena pointwise_data prefetch: no refill loads in the last iteration, so nothing is left in flight at loop exit
# baseline (speedup 1.0000x reference)
; __device__ __forceinline__ void pointwise_data(LAS f32x2* X, const f32x4* Hs, int tid) {
; #pragma unroll 4
;     for (int s = tid; s < 8192; s += NTHR) {
;         const f32x4 hh = Hs[s];
;         if (s == 0) {
;             const f32x2 A = X[0]; const float Y0 = (A.x + A.y) * hh.x, YM = (A.x - A.y) * hh.y; X[0] = (f32x2){0.5f * (Y0 + YM), 0.5f * (Y0 - YM)};
;             const f32x2 Cm = X[1]; const f32x2 Y = cmul((f32x2){Cm.x, -Cm.y}, (f32x2){hh.z, hh.w}); X[1] = (f32x2){Y.x, -Y.y};
;         } else {
;             const int i1 = 2 * s, i2 = i1 ^ ((1 << (31 - __clz(i1))) - 1); const int p = (int)(__brev((unsigned)i1) >> 18);
;             const f32x2 A = X[i1], B = X[i2];
;             const f32x2 E = {0.5f * (A.x + B.x), 0.5f * (A.y - B.y)}; const f32x2 Dm = {A.x - B.x, A.y + B.y}; const f32x2 O = {0.5f * Dm.y, -0.5f * Dm.x};
;             const float rev = (float)p * (1.f / 32768.f); const float c = __builtin_amdgcn_cosf(rev), sn = __builtin_amdgcn_sinf(rev);
;             const f32x2 WO = cmul((f32x2){c, -sn}, O);
;             const f32x2 Xk = E + WO; const f32x2 Xk2 = {E.x - WO.x, -(E.y - WO.y)};
;             const f32x2 Yk = cmul(Xk, (f32x2){hh.x, hh.y}), Yk2 = cmul(Xk2, (f32x2){hh.z, hh.w});
;             const f32x2 Ye = {0.5f * (Yk.x + Yk2.x), 0.5f * (Yk.y - Yk2.y)}; const f32x2 Dd = {Yk.x - Yk2.x, Yk.y + Yk2.y};
;             const f32x2 Yo = cmul((f32x2){0.5f * c, 0.5f * sn}, Dd);
;             X[i1] = (f32x2){Ye.x - Yo.y, Ye.y + Yo.x}; X[i2] = (f32x2){Ye.x + Yo.y, Yo.x - Ye.y};
.LBB0_111:
	s_nop 1
	v_readfirstlane_b32 s2, v4
	s_cmp_gt_u32 s2, 0x17ff
	s_cselect_b32 s2, 1, 0
	s_cmp_lg_u32 s2, 0
	s_cbranch_scc1 .Lhy111_last_0
	s_waitcnt vmcnt(3)
	v_mov_b32_e32 v0, v228
	v_mov_b32_e32 v1, v229
	v_mov_b32_e32 v2, v230
	v_mov_b32_e32 v3, v231
	v_add_co_u32_e32 v244, vcc, 0x2000, v6
	s_nop 1
	v_addc_co_u32_e32 v245, vcc, 0, v7, vcc
	global_load_dwordx4 v[228:231], v[244:245], off
	s_branch .Lhy111_join_0
.Lhy111_last_0:
	s_waitcnt vmcnt(0)
	v_mov_b32_e32 v0, v228
	v_mov_b32_e32 v1, v229
	v_mov_b32_e32 v2, v230
	v_mov_b32_e32 v3, v231
.Lhy111_join_0:
	v_cmp_ne_u32_e32 vcc, 0, v4
	s_and_saveexec_b64 s[0:1], vcc
	s_xor_b64 s[74:75], exec, s[0:1]
	s_cbranch_execz .LBB0_113
	v_add_u32_e32 v5, 0xfffff400, v9
	v_ffbh_u32_e32 v10, v5
	v_lshrrev_b32_e64 v10, v10, s62
	v_add_u32_e32 v10, -1, v10
	v_xor_b32_e32 v22, v10, v5
	v_bfrev_b32_e32 v5, v5
	v_lshrrev_b32_e32 v5, 18, v5
	v_lshl_add_u32 v51, v22, 3, 0
	v_cvt_f32_u32_e32 v5, v5
	ds_read_b64 v[10:11], v8
	ds_read_b64 v[22:23], v51
	v_mul_f32_e32 v5, 0x38000000, v5
	v_cos_f32_e32 v162, v5
	s_waitcnt lgkmcnt(0)
	v_pk_add_f32 v[38:39], v[10:11], v[22:23] neg_lo:[0,1] neg_hi:[0,1]
	v_pk_add_f32 v[10:11], v[10:11], v[22:23]
	v_sin_f32_e32 v22, v5
	v_mul_f32_e32 v166, -0.5, v38
	v_mov_b32_e32 v23, v162
	v_mul_f32_e32 v164, 0.5, v11
	v_xor_b32_e32 v163, 0x80000000, v22
	v_pk_mul_f32 v[166:167], v[22:23], v[166:167] op_sel_hi:[1,0]
	v_pk_mov_b32 v[10:11], v[38:39], v[10:11] op_sel:[1,0]
	v_pk_fma_f32 v[164:165], v[162:163], v[164:165], v[166:167] op_sel_hi:[1,0,1]
	v_pk_mul_f32 v[38:39], v[10:11], 0.5 op_sel_hi:[1,0]
	v_pk_fma_f32 v[10:11], v[10:11], 0.5, v[164:165] op_sel:[0,0,1] op_sel_hi:[1,0,0] neg_lo:[0,0,1] neg_hi:[0,0,1]
	v_pk_add_f32 v[38:39], v[38:39], v[164:165] op_sel:[1,0] op_sel_hi:[0,1]
	v_xor_b32_e32 v166, 0x80000000, v39
	v_mov_b32_e32 v167, v38
	v_pk_mul_f32 v[166:167], v[0:1], v[166:167] op_sel:[1,0]
	v_xor_b32_e32 v165, 0x80000000, v10
	v_pk_fma_f32 v[0:1], v[0:1], v[38:39], v[166:167] op_sel_hi:[0,1,1]
	v_mov_b32_e32 v38, v3
	v_mov_b32_e32 v164, v11
	v_pk_mul_f32 v[10:11], v[38:39], v[10:11] op_sel_hi:[0,1]
	v_pk_fma_f32 v[2:3], v[2:3], v[164:165], v[10:11] op_sel_hi:[0,1,1]
	v_mov_b32_e32 v163, v22
	v_pk_add_f32 v[10:11], v[0:1], v[2:3] neg_lo:[0,1] neg_hi:[0,1]
	v_pk_add_f32 v[0:1], v[0:1], v[2:3]
	v_pk_mul_f32 v[2:3], v[162:163], 0.5 op_sel_hi:[1,0]
	s_nop 0
	v_xor_b32_e32 v22, 0x80000000, v3
	v_mov_b32_e32 v23, v2
	v_pk_mul_f32 v[22:23], v[22:23], v[0:1] op_sel:[0,1]
	s_nop 0
	v_pk_fma_f32 v[2:3], v[2:3], v[10:11], v[22:23] op_sel_hi:[1,0,1]
	v_mov_b32_e32 v10, v0
	v_pk_fma_f32 v[0:1], v[0:1], 0.5, v[2:3] op_sel:[0,0,1] op_sel_hi:[1,0,0] neg_lo:[0,0,1] neg_hi:[0,0,1]
	v_pk_fma_f32 v[22:23], v[10:11], 0.5, v[2:3] op_sel:[0,0,1] op_sel_hi:[1,0,0]
	s_nop 0
	v_mov_b32_e32 v1, v23
	ds_write_b64 v8, v[0:1]
	v_pk_fma_f32 v[0:1], v[10:11], 0.5, v[2:3] op_sel_hi:[1,0,0] neg_lo:[1,0,0] neg_hi:[1,0,0]
	s_nop 0
	v_mov_b32_e32 v23, v1
	ds_write_b64 v51, v[22:23]

; __device__ __forceinline__ void pointwise_data(LAS f32x2* X, const f32x4* Hs, int tid) {
; #pragma unroll 4
;     for (int s = tid; s < 8192; s += NTHR) {
;         const f32x4 hh = Hs[s];
;         if (s == 0) {
;             const f32x2 A = X[0]; const float Y0 = (A.x + A.y) * hh.x, YM = (A.x - A.y) * hh.y; X[0] = (f32x2){0.5f * (Y0 + YM), 0.5f * (Y0 - YM)};
;             const f32x2 Cm = X[1]; const f32x2 Y = cmul((f32x2){Cm.x, -Cm.y}, (f32x2){hh.z, hh.w}); X[1] = (f32x2){Y.x, -Y.y};
;         } else {
;             const int i1 = 2 * s, i2 = i1 ^ ((1 << (31 - __clz(i1))) - 1); const int p = (int)(__brev((unsigned)i1) >> 18);
;             const f32x2 A = X[i1], B = X[i2];
;             const f32x2 E = {0.5f * (A.x + B.x), 0.5f * (A.y - B.y)}; const f32x2 Dm = {A.x - B.x, A.y + B.y}; const f32x2 O = {0.5f * Dm.y, -0.5f * Dm.x};
;             const float rev = (float)p * (1.f / 32768.f); const float c = __builtin_amdgcn_cosf(rev), sn = __builtin_amdgcn_sinf(rev);
;             const f32x2 WO = cmul((f32x2){c, -sn}, O);
;             const f32x2 Xk = E + WO; const f32x2 Xk2 = {E.x - WO.x, -(E.y - WO.y)};
;             const f32x2 Yk = cmul(Xk, (f32x2){hh.x, hh.y}), Yk2 = cmul(Xk2, (f32x2){hh.z, hh.w});
;             const f32x2 Ye = {0.5f * (Yk.x + Yk2.x), 0.5f * (Yk.y - Yk2.y)}; const f32x2 Dd = {Yk.x - Yk2.x, Yk.y + Yk2.y};
;             const f32x2 Yo = cmul((f32x2){0.5f * c, 0.5f * sn}, Dd);
;             X[i1] = (f32x2){Ye.x - Yo.y, Ye.y + Yo.x}; X[i2] = (f32x2){Ye.x + Yo.y, Yo.x - Ye.y};
.LBB0_115:
	s_or_b64 exec, exec, s[74:75]
	v_add_u32_e32 v5, 0x200, v4
	s_nop 0
	s_cmp_lg_u32 s2, 0
	s_cbranch_scc1 .Lhy111_last_1
	s_waitcnt vmcnt(3)
	v_mov_b32_e32 v0, v232
	v_mov_b32_e32 v1, v233
	v_mov_b32_e32 v2, v234
	v_mov_b32_e32 v3, v235
	v_add_co_u32_e32 v244, vcc, 0x4000, v6
	s_nop 1
	v_addc_co_u32_e32 v245, vcc, 0, v7, vcc
	global_load_dwordx4 v[232:235], v[244:245], off
	s_branch .Lhy111_join_1
.Lhy111_last_1:
	s_waitcnt vmcnt(0)
	v_mov_b32_e32 v0, v232
	v_mov_b32_e32 v1, v233
	v_mov_b32_e32 v2, v234
	v_mov_b32_e32 v3, v235
.Lhy111_join_1:
	v_cmp_ne_u32_e32 vcc, 0, v5
	s_and_saveexec_b64 s[0:1], vcc
	s_xor_b64 s[74:75], exec, s[0:1]
	s_cbranch_execz .LBB0_117
	v_add_u32_e32 v38, 0xfffff800, v9
	v_ffbh_u32_e32 v10, v38
	v_lshrrev_b32_e64 v10, v10, s62
	v_add_u32_e32 v10, -1, v10
	v_xor_b32_e32 v22, v10, v38
	v_lshl_add_u32 v51, v22, 3, 0
	v_bfrev_b32_e32 v38, v38
	ds_read_b64 v[10:11], v8 offset:8192
	ds_read_b64 v[22:23], v51
	v_lshrrev_b32_e32 v38, 18, v38
	v_cvt_f32_u32_e32 v53, v38
	s_waitcnt lgkmcnt(0)
	v_pk_add_f32 v[38:39], v[10:11], v[22:23] neg_lo:[0,1] neg_hi:[0,1]
	v_pk_add_f32 v[10:11], v[10:11], v[22:23]
	v_mul_f32_e32 v23, 0x38000000, v53
	v_cos_f32_e32 v162, v23
	v_sin_f32_e32 v22, v23
	v_mul_f32_e32 v166, -0.5, v38
	v_mul_f32_e32 v164, 0.5, v11
	v_mov_b32_e32 v23, v162
	v_xor_b32_e32 v163, 0x80000000, v22
	v_pk_mul_f32 v[166:167], v[22:23], v[166:167] op_sel_hi:[1,0]
	v_pk_mov_b32 v[10:11], v[38:39], v[10:11] op_sel:[1,0]
	v_pk_fma_f32 v[164:165], v[162:163], v[164:165], v[166:167] op_sel_hi:[1,0,1]
	v_pk_mul_f32 v[38:39], v[10:11], 0.5 op_sel_hi:[1,0]
	v_pk_fma_f32 v[10:11], v[10:11], 0.5, v[164:165] op_sel:[0,0,1] op_sel_hi:[1,0,0] neg_lo:[0,0,1] neg_hi:[0,0,1]
	v_pk_add_f32 v[38:39], v[38:39], v[164:165] op_sel:[1,0] op_sel_hi:[0,1]
	v_xor_b32_e32 v166, 0x80000000, v39
	v_mov_b32_e32 v167, v38
	v_pk_mul_f32 v[166:167], v[0:1], v[166:167] op_sel:[1,0]
	v_xor_b32_e32 v165, 0x80000000, v10
	v_pk_fma_f32 v[0:1], v[0:1], v[38:39], v[166:167] op_sel_hi:[0,1,1]
	v_mov_b32_e32 v38, v3
	v_mov_b32_e32 v164, v11
	v_pk_mul_f32 v[10:11], v[38:39], v[10:11] op_sel_hi:[0,1]
	v_pk_fma_f32 v[2:3], v[2:3], v[164:165], v[10:11] op_sel_hi:[0,1,1]
	v_mov_b32_e32 v163, v22
	v_pk_add_f32 v[10:11], v[0:1], v[2:3] neg_lo:[0,1] neg_hi:[0,1]
	v_pk_add_f32 v[0:1], v[0:1], v[2:3]
	v_pk_mul_f32 v[2:3], v[162:163], 0.5 op_sel_hi:[1,0]
	s_nop 0
	v_xor_b32_e32 v22, 0x80000000, v3
	v_mov_b32_e32 v23, v2
	v_pk_mul_f32 v[22:23], v[22:23], v[0:1] op_sel:[0,1]
	s_nop 0
	v_pk_fma_f32 v[2:3], v[2:3], v[10:11], v[22:23] op_sel_hi:[1,0,1]
	v_mov_b32_e32 v10, v0
	v_pk_fma_f32 v[0:1], v[0:1], 0.5, v[2:3] op_sel:[0,0,1] op_sel_hi:[1,0,0] neg_lo:[0,0,1] neg_hi:[0,0,1]
	v_pk_fma_f32 v[22:23], v[10:11], 0.5, v[2:3] op_sel:[0,0,1] op_sel_hi:[1,0,0]
	s_nop 0
	v_mov_b32_e32 v1, v23
	ds_write_b64 v8, v[0:1] offset:8192
	v_pk_fma_f32 v[0:1], v[10:11], 0.5, v[2:3] op_sel_hi:[1,0,0] neg_lo:[1,0,0] neg_hi:[1,0,0]
	s_nop 0
	v_mov_b32_e32 v23, v1
	ds_write_b64 v51, v[22:23]

; __device__ __forceinline__ void pointwise_data(LAS f32x2* X, const f32x4* Hs, int tid) {
; #pragma unroll 4
;     for (int s = tid; s < 8192; s += NTHR) {
;         const f32x4 hh = Hs[s];
;         if (s == 0) {
;             const f32x2 A = X[0]; const float Y0 = (A.x + A.y) * hh.x, YM = (A.x - A.y) * hh.y; X[0] = (f32x2){0.5f * (Y0 + YM), 0.5f * (Y0 - YM)};
;             const f32x2 Cm = X[1]; const f32x2 Y = cmul((f32x2){Cm.x, -Cm.y}, (f32x2){hh.z, hh.w}); X[1] = (f32x2){Y.x, -Y.y};
;         } else {
;             const int i1 = 2 * s, i2 = i1 ^ ((1 << (31 - __clz(i1))) - 1); const int p = (int)(__brev((unsigned)i1) >> 18);
;             const f32x2 A = X[i1], B = X[i2];
;             const f32x2 E = {0.5f * (A.x + B.x), 0.5f * (A.y - B.y)}; const f32x2 Dm = {A.x - B.x, A.y + B.y}; const f32x2 O = {0.5f * Dm.y, -0.5f * Dm.x};
;             const float rev = (float)p * (1.f / 32768.f); const float c = __builtin_amdgcn_cosf(rev), sn = __builtin_amdgcn_sinf(rev);
;             const f32x2 WO = cmul((f32x2){c, -sn}, O);
;             const f32x2 Xk = E + WO; const f32x2 Xk2 = {E.x - WO.x, -(E.y - WO.y)};
;             const f32x2 Yk = cmul(Xk, (f32x2){hh.x, hh.y}), Yk2 = cmul(Xk2, (f32x2){hh.z, hh.w});
;             const f32x2 Ye = {0.5f * (Yk.x + Yk2.x), 0.5f * (Yk.y - Yk2.y)}; const f32x2 Dd = {Yk.x - Yk2.x, Yk.y + Yk2.y};
;             const f32x2 Yo = cmul((f32x2){0.5f * c, 0.5f * sn}, Dd);
;             X[i1] = (f32x2){Ye.x - Yo.y, Ye.y + Yo.x}; X[i2] = (f32x2){Ye.x + Yo.y, Yo.x - Ye.y};
.LBB0_119:
	s_or_b64 exec, exec, s[74:75]
	v_add_u32_e32 v5, 0x200, v5
	s_nop 0
	s_cmp_lg_u32 s2, 0
	s_cbranch_scc1 .Lhy111_last_2
	s_waitcnt vmcnt(3)
	v_mov_b32_e32 v0, v236
	v_mov_b32_e32 v1, v237
	v_mov_b32_e32 v2, v238
	v_mov_b32_e32 v3, v239
	v_add_co_u32_e32 v244, vcc, 0x6000, v6
	s_nop 1
	v_addc_co_u32_e32 v245, vcc, 0, v7, vcc
	global_load_dwordx4 v[236:239], v[244:245], off
	s_branch .Lhy111_join_2
.Lhy111_last_2:
	s_waitcnt vmcnt(0)
	v_mov_b32_e32 v0, v236
	v_mov_b32_e32 v1, v237
	v_mov_b32_e32 v2, v238
	v_mov_b32_e32 v3, v239
.Lhy111_join_2:
	v_cmp_ne_u32_e32 vcc, 0, v5
	s_and_saveexec_b64 s[0:1], vcc
	s_xor_b64 s[74:75], exec, s[0:1]
	s_cbranch_execz .LBB0_121
	v_add_u32_e32 v38, 0xfffffc00, v9
	v_ffbh_u32_e32 v10, v38
	v_lshrrev_b32_e64 v10, v10, s62
	v_add_u32_e32 v10, -1, v10
	v_xor_b32_e32 v22, v10, v38
	v_lshl_add_u32 v51, v22, 3, 0
	v_bfrev_b32_e32 v38, v38
	ds_read_b64 v[10:11], v8 offset:16384
	ds_read_b64 v[22:23], v51
	v_lshrrev_b32_e32 v38, 18, v38
	v_cvt_f32_u32_e32 v53, v38
	s_waitcnt lgkmcnt(0)
	v_pk_add_f32 v[38:39], v[10:11], v[22:23] neg_lo:[0,1] neg_hi:[0,1]
	v_pk_add_f32 v[10:11], v[10:11], v[22:23]
	v_mul_f32_e32 v23, 0x38000000, v53
	v_cos_f32_e32 v162, v23
	v_sin_f32_e32 v22, v23
	v_mul_f32_e32 v166, -0.5, v38
	v_mul_f32_e32 v164, 0.5, v11
	v_mov_b32_e32 v23, v162
	v_xor_b32_e32 v163, 0x80000000, v22
	v_pk_mul_f32 v[166:167], v[22:23], v[166:167] op_sel_hi:[1,0]
	v_pk_mov_b32 v[10:11], v[38:39], v[10:11] op_sel:[1,0]
	v_pk_fma_f32 v[164:165], v[162:163], v[164:165], v[166:167] op_sel_hi:[1,0,1]
	v_pk_mul_f32 v[38:39], v[10:11], 0.5 op_sel_hi:[1,0]
	v_pk_fma_f32 v[10:11], v[10:11], 0.5, v[164:165] op_sel:[0,0,1] op_sel_hi:[1,0,0] neg_lo:[0,0,1] neg_hi:[0,0,1]
	v_pk_add_f32 v[38:39], v[38:39], v[164:165] op_sel:[1,0] op_sel_hi:[0,1]
	v_xor_b32_e32 v166, 0x80000000, v39
	v_mov_b32_e32 v167, v38
	v_pk_mul_f32 v[166:167], v[0:1], v[166:167] op_sel:[1,0]
	v_xor_b32_e32 v165, 0x80000000, v10
	v_pk_fma_f32 v[0:1], v[0:1], v[38:39], v[166:167] op_sel_hi:[0,1,1]
	v_mov_b32_e32 v38, v3
	v_mov_b32_e32 v164, v11
	v_pk_mul_f32 v[10:11], v[38:39], v[10:11] op_sel_hi:[0,1]
	v_pk_fma_f32 v[2:3], v[2:3], v[164:165], v[10:11] op_sel_hi:[0,1,1]
	v_mov_b32_e32 v163, v22
	v_pk_add_f32 v[10:11], v[0:1], v[2:3] neg_lo:[0,1] neg_hi:[0,1]
	v_pk_add_f32 v[0:1], v[0:1], v[2:3]
	v_pk_mul_f32 v[2:3], v[162:163], 0.5 op_sel_hi:[1,0]
	s_nop 0
	v_xor_b32_e32 v22, 0x80000000, v3
	v_mov_b32_e32 v23, v2
	v_pk_mul_f32 v[22:23], v[22:23], v[0:1] op_sel:[0,1]
	s_nop 0
	v_pk_fma_f32 v[2:3], v[2:3], v[10:11], v[22:23] op_sel_hi:[1,0,1]
	v_mov_b32_e32 v10, v0
	v_pk_fma_f32 v[0:1], v[0:1], 0.5, v[2:3] op_sel:[0,0,1] op_sel_hi:[1,0,0] neg_lo:[0,0,1] neg_hi:[0,0,1]
	v_pk_fma_f32 v[22:23], v[10:11], 0.5, v[2:3] op_sel:[0,0,1] op_sel_hi:[1,0,0]
	s_nop 0
	v_mov_b32_e32 v1, v23
	ds_write_b64 v8, v[0:1] offset:16384
	v_pk_fma_f32 v[0:1], v[10:11], 0.5, v[2:3] op_sel_hi:[1,0,0] neg_lo:[1,0,0] neg_hi:[1,0,0]
	s_nop 0
	v_mov_b32_e32 v23, v1
	ds_write_b64 v51, v[22:23]

; __device__ __forceinline__ void pointwise_data(LAS f32x2* X, const f32x4* Hs, int tid) {
; #pragma unroll 4
;     for (int s = tid; s < 8192; s += NTHR) {
;         const f32x4 hh = Hs[s];
;         if (s == 0) {
;             const f32x2 A = X[0]; const float Y0 = (A.x + A.y) * hh.x, YM = (A.x - A.y) * hh.y; X[0] = (f32x2){0.5f * (Y0 + YM), 0.5f * (Y0 - YM)};
;             const f32x2 Cm = X[1]; const f32x2 Y = cmul((f32x2){Cm.x, -Cm.y}, (f32x2){hh.z, hh.w}); X[1] = (f32x2){Y.x, -Y.y};
;         } else {
;             const int i1 = 2 * s, i2 = i1 ^ ((1 << (31 - __clz(i1))) - 1); const int p = (int)(__brev((unsigned)i1) >> 18);
;             const f32x2 A = X[i1], B = X[i2];
;             const f32x2 E = {0.5f * (A.x + B.x), 0.5f * (A.y - B.y)}; const f32x2 Dm = {A.x - B.x, A.y + B.y}; const f32x2 O = {0.5f * Dm.y, -0.5f * Dm.x};
;             const float rev = (float)p * (1.f / 32768.f); const float c = __builtin_amdgcn_cosf(rev), sn = __builtin_amdgcn_sinf(rev);
;             const f32x2 WO = cmul((f32x2){c, -sn}, O);
;             const f32x2 Xk = E + WO; const f32x2 Xk2 = {E.x - WO.x, -(E.y - WO.y)};
;             const f32x2 Yk = cmul(Xk, (f32x2){hh.x, hh.y}), Yk2 = cmul(Xk2, (f32x2){hh.z, hh.w});
;             const f32x2 Ye = {0.5f * (Yk.x + Yk2.x), 0.5f * (Yk.y - Yk2.y)}; const f32x2 Dd = {Yk.x - Yk2.x, Yk.y + Yk2.y};
;             const f32x2 Yo = cmul((f32x2){0.5f * c, 0.5f * sn}, Dd);
;             X[i1] = (f32x2){Ye.x - Yo.y, Ye.y + Yo.x}; X[i2] = (f32x2){Ye.x + Yo.y, Yo.x - Ye.y};
.LBB0_123:
	s_or_b64 exec, exec, s[74:75]
	s_cmp_lg_u32 s2, 0
	s_cbranch_scc1 .Lhy111_last_3
	s_waitcnt vmcnt(3)
	v_mov_b32_e32 v0, v240
	v_mov_b32_e32 v1, v241
	v_mov_b32_e32 v2, v242
	v_mov_b32_e32 v3, v243
	v_add_co_u32_e32 v244, vcc, 0x8000, v6
	s_nop 1
	v_addc_co_u32_e32 v245, vcc, 0, v7, vcc
	global_load_dwordx4 v[240:243], v[244:245], off
	s_branch .Lhy111_join_3
.Lhy111_last_3:
	s_waitcnt vmcnt(0)
	v_mov_b32_e32 v0, v240
	v_mov_b32_e32 v1, v241
	v_mov_b32_e32 v2, v242
	v_mov_b32_e32 v3, v243
.Lhy111_join_3:
	v_cmp_ne_u32_e32 vcc, s83, v5
	s_and_saveexec_b64 s[0:1], vcc
	s_xor_b64 s[74:75], exec, s[0:1]
	s_cbranch_execz .LBB0_125
	v_ffbh_u32_e32 v5, v9
	v_lshrrev_b32_e64 v5, v5, s62
	v_add_u32_e32 v5, -1, v5
	v_xor_b32_e32 v5, v5, v9
	v_lshl_add_u32 v5, v5, 3, 0
	v_bfrev_b32_e32 v38, v9
	ds_read_b64 v[10:11], v8 offset:24576
	ds_read_b64 v[22:23], v5
	v_lshrrev_b32_e32 v38, 18, v38
	v_cvt_f32_u32_e32 v51, v38
	s_waitcnt lgkmcnt(0)
	v_pk_add_f32 v[38:39], v[10:11], v[22:23] neg_lo:[0,1] neg_hi:[0,1]
	v_pk_add_f32 v[10:11], v[10:11], v[22:23]
	v_mul_f32_e32 v23, 0x38000000, v51
	v_cos_f32_e32 v162, v23
	v_sin_f32_e32 v22, v23
	v_mul_f32_e32 v166, -0.5, v38
	v_mul_f32_e32 v164, 0.5, v11
	v_mov_b32_e32 v23, v162
	v_xor_b32_e32 v163, 0x80000000, v22
	v_pk_mul_f32 v[166:167], v[22:23], v[166:167] op_sel_hi:[1,0]
	v_pk_mov_b32 v[10:11], v[38:39], v[10:11] op_sel:[1,0]
	v_pk_fma_f32 v[164:165], v[162:163], v[164:165], v[166:167] op_sel_hi:[1,0,1]
	v_pk_mul_f32 v[38:39], v[10:11], 0.5 op_sel_hi:[1,0]
	v_pk_fma_f32 v[10:11], v[10:11], 0.5, v[164:165] op_sel:[0,0,1] op_sel_hi:[1,0,0] neg_lo:[0,0,1] neg_hi:[0,0,1]
	v_pk_add_f32 v[38:39], v[38:39], v[164:165] op_sel:[1,0] op_sel_hi:[0,1]
	v_xor_b32_e32 v166, 0x80000000, v39
	v_mov_b32_e32 v167, v38
	v_pk_mul_f32 v[166:167], v[0:1], v[166:167] op_sel:[1,0]
	v_xor_b32_e32 v165, 0x80000000, v10
	v_pk_fma_f32 v[0:1], v[0:1], v[38:39], v[166:167] op_sel_hi:[0,1,1]
	v_mov_b32_e32 v38, v3
	v_mov_b32_e32 v164, v11
	v_pk_mul_f32 v[10:11], v[38:39], v[10:11] op_sel_hi:[0,1]
	v_pk_fma_f32 v[2:3], v[2:3], v[164:165], v[10:11] op_sel_hi:[0,1,1]
	v_mov_b32_e32 v163, v22
	v_pk_add_f32 v[10:11], v[0:1], v[2:3] neg_lo:[0,1] neg_hi:[0,1]
	v_pk_add_f32 v[0:1], v[0:1], v[2:3]
	v_pk_mul_f32 v[2:3], v[162:163], 0.5 op_sel_hi:[1,0]
	s_nop 0
	v_xor_b32_e32 v22, 0x80000000, v3
	v_mov_b32_e32 v23, v2
	v_pk_mul_f32 v[22:23], v[22:23], v[0:1] op_sel:[0,1]
	s_nop 0
	v_pk_fma_f32 v[2:3], v[2:3], v[10:11], v[22:23] op_sel_hi:[1,0,1]
	v_mov_b32_e32 v10, v0
	v_pk_fma_f32 v[0:1], v[0:1], 0.5, v[2:3] op_sel:[0,0,1] op_sel_hi:[1,0,0] neg_lo:[0,0,1] neg_hi:[0,0,1]
	v_pk_fma_f32 v[22:23], v[10:11], 0.5, v[2:3] op_sel:[0,0,1] op_sel_hi:[1,0,0]
	s_nop 0
	v_mov_b32_e32 v1, v23
	ds_write_b64 v8, v[0:1] offset:24576
	v_pk_fma_f32 v[0:1], v[10:11], 0.5, v[2:3] op_sel_hi:[1,0,0] neg_lo:[1,0,0] neg_hi:[1,0,0]
	s_nop 0
	v_mov_b32_e32 v23, v1
	ds_write_b64 v5, v[22:23]

; __device__ __forceinline__ void pointwise_data(LAS f32x2* X, const f32x4* Hs, int tid) {
; #pragma unroll 4
;     for (int s = tid; s < 8192; s += NTHR) {
;         const f32x4 hh = Hs[s];
;         if (s == 0) {
;             const f32x2 A = X[0]; const float Y0 = (A.x + A.y) * hh.x, YM = (A.x - A.y) * hh.y; X[0] = (f32x2){0.5f * (Y0 + YM), 0.5f * (Y0 - YM)};
;             const f32x2 Cm = X[1]; const f32x2 Y = cmul((f32x2){Cm.x, -Cm.y}, (f32x2){hh.z, hh.w}); X[1] = (f32x2){Y.x, -Y.y};
;         } else {
;             const int i1 = 2 * s, i2 = i1 ^ ((1 << (31 - __clz(i1))) - 1); const int p = (int)(__brev((unsigned)i1) >> 18);
;             const f32x2 A = X[i1], B = X[i2];
;             const f32x2 E = {0.5f * (A.x + B.x), 0.5f * (A.y - B.y)}; const f32x2 Dm = {A.x - B.x, A.y + B.y}; const f32x2 O = {0.5f * Dm.y, -0.5f * Dm.x};
;             const float rev = (float)p * (1.f / 32768.f); const float c = __builtin_amdgcn_cosf(rev), sn = __builtin_amdgcn_sinf(rev);
;             const f32x2 WO = cmul((f32x2){c, -sn}, O);
;             const f32x2 Xk = E + WO; const f32x2 Xk2 = {E.x - WO.x, -(E.y - WO.y)};
;             const f32x2 Yk = cmul(Xk, (f32x2){hh.x, hh.y}), Yk2 = cmul(Xk2, (f32x2){hh.z, hh.w});
;             const f32x2 Ye = {0.5f * (Yk.x + Yk2.x), 0.5f * (Yk.y - Yk2.y)}; const f32x2 Dd = {Yk.x - Yk2.x, Yk.y + Yk2.y};
;             const f32x2 Yo = cmul((f32x2){0.5f * c, 0.5f * sn}, Dd);
;             X[i1] = (f32x2){Ye.x - Yo.y, Ye.y + Yo.x}; X[i2] = (f32x2){Ye.x + Yo.y, Yo.x - Ye.y};
.LBB0_174:
	s_nop 1
	v_readfirstlane_b32 s2, v4
	s_cmp_gt_u32 s2, 0x17ff
	s_cselect_b32 s2, 1, 0
	s_cmp_lg_u32 s2, 0
	s_cbranch_scc1 .Lhy174_last_0
	s_waitcnt vmcnt(3)
	v_mov_b32_e32 v0, v24
	v_mov_b32_e32 v1, v25
	v_mov_b32_e32 v2, v26
	v_mov_b32_e32 v3, v27
	v_add_co_u32_e32 v162, vcc, 0x2000, v6
	s_nop 1
	v_addc_co_u32_e32 v163, vcc, 0, v7, vcc
	global_load_dwordx4 v[24:27], v[162:163], off
	s_branch .Lhy174_join_0
.Lhy174_last_0:
	s_waitcnt vmcnt(0)
	v_mov_b32_e32 v0, v24
	v_mov_b32_e32 v1, v25
	v_mov_b32_e32 v2, v26
	v_mov_b32_e32 v3, v27
.Lhy174_join_0:
	v_cmp_ne_u32_e32 vcc, 0, v4
	s_and_saveexec_b64 s[0:1], vcc
	s_xor_b64 s[74:75], exec, s[0:1]
	s_cbranch_execz .LBB0_176
	v_add_u32_e32 v5, 0xfffff400, v9
	v_ffbh_u32_e32 v10, v5
	v_lshrrev_b32_e64 v10, v10, s62
	v_add_u32_e32 v10, -1, v10
	v_xor_b32_e32 v12, v10, v5
	v_bfrev_b32_e32 v5, v5
	v_lshrrev_b32_e32 v5, 18, v5
	v_lshl_add_u32 v22, v12, 3, 0
	v_cvt_f32_u32_e32 v5, v5
	ds_read_b64 v[10:11], v8
	ds_read_b64 v[12:13], v22
	v_mul_f32_e32 v5, 0x38000000, v5
	v_cos_f32_e32 v16, v5
	s_waitcnt lgkmcnt(0)
	v_pk_add_f32 v[14:15], v[10:11], v[12:13] neg_lo:[0,1] neg_hi:[0,1]
	v_pk_add_f32 v[10:11], v[10:11], v[12:13]
	v_sin_f32_e32 v12, v5
	v_mul_f32_e32 v20, -0.5, v14
	v_mov_b32_e32 v13, v16
	v_mul_f32_e32 v18, 0.5, v11
	v_xor_b32_e32 v17, 0x80000000, v12
	v_pk_mul_f32 v[20:21], v[12:13], v[20:21] op_sel_hi:[1,0]
	v_pk_mov_b32 v[10:11], v[14:15], v[10:11] op_sel:[1,0]
	v_pk_fma_f32 v[18:19], v[16:17], v[18:19], v[20:21] op_sel_hi:[1,0,1]
	v_pk_mul_f32 v[14:15], v[10:11], 0.5 op_sel_hi:[1,0]
	v_pk_fma_f32 v[10:11], v[10:11], 0.5, v[18:19] op_sel:[0,0,1] op_sel_hi:[1,0,0] neg_lo:[0,0,1] neg_hi:[0,0,1]
	v_pk_add_f32 v[14:15], v[14:15], v[18:19] op_sel:[1,0] op_sel_hi:[0,1]
	v_xor_b32_e32 v20, 0x80000000, v15
	v_mov_b32_e32 v21, v14
	v_pk_mul_f32 v[20:21], v[0:1], v[20:21] op_sel:[1,0]
	v_xor_b32_e32 v19, 0x80000000, v10
	v_pk_fma_f32 v[0:1], v[0:1], v[14:15], v[20:21] op_sel_hi:[0,1,1]
	v_mov_b32_e32 v14, v3
	v_mov_b32_e32 v18, v11
	v_pk_mul_f32 v[10:11], v[14:15], v[10:11] op_sel_hi:[0,1]
	v_pk_fma_f32 v[2:3], v[2:3], v[18:19], v[10:11] op_sel_hi:[0,1,1]
	v_mov_b32_e32 v17, v12
	v_pk_add_f32 v[10:11], v[0:1], v[2:3] neg_lo:[0,1] neg_hi:[0,1]
	v_pk_add_f32 v[0:1], v[0:1], v[2:3]
	v_pk_mul_f32 v[2:3], v[16:17], 0.5 op_sel_hi:[1,0]
	s_nop 0
	v_xor_b32_e32 v12, 0x80000000, v3
	v_mov_b32_e32 v13, v2
	v_pk_mul_f32 v[12:13], v[12:13], v[0:1] op_sel:[0,1]
	s_nop 0
	v_pk_fma_f32 v[2:3], v[2:3], v[10:11], v[12:13] op_sel_hi:[1,0,1]
	v_mov_b32_e32 v10, v0
	v_pk_fma_f32 v[0:1], v[0:1], 0.5, v[2:3] op_sel:[0,0,1] op_sel_hi:[1,0,0] neg_lo:[0,0,1] neg_hi:[0,0,1]
	v_pk_fma_f32 v[12:13], v[10:11], 0.5, v[2:3] op_sel:[0,0,1] op_sel_hi:[1,0,0]
	s_nop 0
	v_mov_b32_e32 v1, v13
	ds_write_b64 v8, v[0:1]
	v_pk_fma_f32 v[0:1], v[10:11], 0.5, v[2:3] op_sel_hi:[1,0,0] neg_lo:[1,0,0] neg_hi:[1,0,0]
	s_nop 0
	v_mov_b32_e32 v13, v1
	ds_write_b64 v22, v[12:13]

; __device__ __forceinline__ void pointwise_data(LAS f32x2* X, const f32x4* Hs, int tid) {
; #pragma unroll 4
;     for (int s = tid; s < 8192; s += NTHR) {
;         const f32x4 hh = Hs[s];
;         if (s == 0) {
;             const f32x2 A = X[0]; const float Y0 = (A.x + A.y) * hh.x, YM = (A.x - A.y) * hh.y; X[0] = (f32x2){0.5f * (Y0 + YM), 0.5f * (Y0 - YM)};
;             const f32x2 Cm = X[1]; const f32x2 Y = cmul((f32x2){Cm.x, -Cm.y}, (f32x2){hh.z, hh.w}); X[1] = (f32x2){Y.x, -Y.y};
;         } else {
;             const int i1 = 2 * s, i2 = i1 ^ ((1 << (31 - __clz(i1))) - 1); const int p = (int)(__brev((unsigned)i1) >> 18);
;             const f32x2 A = X[i1], B = X[i2];
;             const f32x2 E = {0.5f * (A.x + B.x), 0.5f * (A.y - B.y)}; const f32x2 Dm = {A.x - B.x, A.y + B.y}; const f32x2 O = {0.5f * Dm.y, -0.5f * Dm.x};
;             const float rev = (float)p * (1.f / 32768.f); const float c = __builtin_amdgcn_cosf(rev), sn = __builtin_amdgcn_sinf(rev);
;             const f32x2 WO = cmul((f32x2){c, -sn}, O);
;             const f32x2 Xk = E + WO; const f32x2 Xk2 = {E.x - WO.x, -(E.y - WO.y)};
;             const f32x2 Yk = cmul(Xk, (f32x2){hh.x, hh.y}), Yk2 = cmul(Xk2, (f32x2){hh.z, hh.w});
;             const f32x2 Ye = {0.5f * (Yk.x + Yk2.x), 0.5f * (Yk.y - Yk2.y)}; const f32x2 Dd = {Yk.x - Yk2.x, Yk.y + Yk2.y};
;             const f32x2 Yo = cmul((f32x2){0.5f * c, 0.5f * sn}, Dd);
;             X[i1] = (f32x2){Ye.x - Yo.y, Ye.y + Yo.x}; X[i2] = (f32x2){Ye.x + Yo.y, Yo.x - Ye.y};
.LBB0_178:
	s_or_b64 exec, exec, s[74:75]
	v_add_u32_e32 v5, 0x200, v4
	s_nop 0
	s_cmp_lg_u32 s2, 0
	s_cbranch_scc1 .Lhy174_last_1
	s_waitcnt vmcnt(3)
	v_mov_b32_e32 v0, v28
	v_mov_b32_e32 v1, v29
	v_mov_b32_e32 v2, v30
	v_mov_b32_e32 v3, v31
	v_add_co_u32_e32 v162, vcc, 0x4000, v6
	s_nop 1
	v_addc_co_u32_e32 v163, vcc, 0, v7, vcc
	global_load_dwordx4 v[28:31], v[162:163], off
	s_branch .Lhy174_join_1
.Lhy174_last_1:
	s_waitcnt vmcnt(0)
	v_mov_b32_e32 v0, v28
	v_mov_b32_e32 v1, v29
	v_mov_b32_e32 v2, v30
	v_mov_b32_e32 v3, v31
.Lhy174_join_1:
	v_cmp_ne_u32_e32 vcc, 0, v5
	s_and_saveexec_b64 s[0:1], vcc
	s_xor_b64 s[74:75], exec, s[0:1]
	s_cbranch_execz .LBB0_180
	v_add_u32_e32 v14, 0xfffff800, v9
	v_ffbh_u32_e32 v10, v14
	v_lshrrev_b32_e64 v10, v10, s62
	v_add_u32_e32 v10, -1, v10
	v_xor_b32_e32 v12, v10, v14
	v_lshl_add_u32 v22, v12, 3, 0
	v_bfrev_b32_e32 v14, v14
	ds_read_b64 v[10:11], v8 offset:8192
	ds_read_b64 v[12:13], v22
	v_lshrrev_b32_e32 v14, 18, v14
	v_cvt_f32_u32_e32 v16, v14
	s_waitcnt lgkmcnt(0)
	v_pk_add_f32 v[14:15], v[10:11], v[12:13] neg_lo:[0,1] neg_hi:[0,1]
	v_pk_add_f32 v[10:11], v[10:11], v[12:13]
	v_mul_f32_e32 v13, 0x38000000, v16
	v_cos_f32_e32 v16, v13
	v_sin_f32_e32 v12, v13
	v_mul_f32_e32 v20, -0.5, v14
	v_mul_f32_e32 v18, 0.5, v11
	v_mov_b32_e32 v13, v16
	v_xor_b32_e32 v17, 0x80000000, v12
	v_pk_mul_f32 v[20:21], v[12:13], v[20:21] op_sel_hi:[1,0]
	v_pk_mov_b32 v[10:11], v[14:15], v[10:11] op_sel:[1,0]
	v_pk_fma_f32 v[18:19], v[16:17], v[18:19], v[20:21] op_sel_hi:[1,0,1]
	v_pk_mul_f32 v[14:15], v[10:11], 0.5 op_sel_hi:[1,0]
	v_pk_fma_f32 v[10:11], v[10:11], 0.5, v[18:19] op_sel:[0,0,1] op_sel_hi:[1,0,0] neg_lo:[0,0,1] neg_hi:[0,0,1]
	v_pk_add_f32 v[14:15], v[14:15], v[18:19] op_sel:[1,0] op_sel_hi:[0,1]
	v_xor_b32_e32 v20, 0x80000000, v15
	v_mov_b32_e32 v21, v14
	v_pk_mul_f32 v[20:21], v[0:1], v[20:21] op_sel:[1,0]
	v_xor_b32_e32 v19, 0x80000000, v10
	v_pk_fma_f32 v[0:1], v[0:1], v[14:15], v[20:21] op_sel_hi:[0,1,1]
	v_mov_b32_e32 v14, v3
	v_mov_b32_e32 v18, v11
	v_pk_mul_f32 v[10:11], v[14:15], v[10:11] op_sel_hi:[0,1]
	v_pk_fma_f32 v[2:3], v[2:3], v[18:19], v[10:11] op_sel_hi:[0,1,1]
	v_mov_b32_e32 v17, v12
	v_pk_add_f32 v[10:11], v[0:1], v[2:3] neg_lo:[0,1] neg_hi:[0,1]
	v_pk_add_f32 v[0:1], v[0:1], v[2:3]
	v_pk_mul_f32 v[2:3], v[16:17], 0.5 op_sel_hi:[1,0]
	s_nop 0
	v_xor_b32_e32 v12, 0x80000000, v3
	v_mov_b32_e32 v13, v2
	v_pk_mul_f32 v[12:13], v[12:13], v[0:1] op_sel:[0,1]
	s_nop 0
	v_pk_fma_f32 v[2:3], v[2:3], v[10:11], v[12:13] op_sel_hi:[1,0,1]
	v_mov_b32_e32 v10, v0
	v_pk_fma_f32 v[0:1], v[0:1], 0.5, v[2:3] op_sel:[0,0,1] op_sel_hi:[1,0,0] neg_lo:[0,0,1] neg_hi:[0,0,1]
	v_pk_fma_f32 v[12:13], v[10:11], 0.5, v[2:3] op_sel:[0,0,1] op_sel_hi:[1,0,0]
	s_nop 0
	v_mov_b32_e32 v1, v13
	ds_write_b64 v8, v[0:1] offset:8192
	v_pk_fma_f32 v[0:1], v[10:11], 0.5, v[2:3] op_sel_hi:[1,0,0] neg_lo:[1,0,0] neg_hi:[1,0,0]
	s_nop 0
	v_mov_b32_e32 v13, v1
	ds_write_b64 v22, v[12:13]

; __device__ __forceinline__ void pointwise_data(LAS f32x2* X, const f32x4* Hs, int tid) {
; #pragma unroll 4
;     for (int s = tid; s < 8192; s += NTHR) {
;         const f32x4 hh = Hs[s];
;         if (s == 0) {
;             const f32x2 A = X[0]; const float Y0 = (A.x + A.y) * hh.x, YM = (A.x - A.y) * hh.y; X[0] = (f32x2){0.5f * (Y0 + YM), 0.5f * (Y0 - YM)};
;             const f32x2 Cm = X[1]; const f32x2 Y = cmul((f32x2){Cm.x, -Cm.y}, (f32x2){hh.z, hh.w}); X[1] = (f32x2){Y.x, -Y.y};
;         } else {
;             const int i1 = 2 * s, i2 = i1 ^ ((1 << (31 - __clz(i1))) - 1); const int p = (int)(__brev((unsigned)i1) >> 18);
;             const f32x2 A = X[i1], B = X[i2];
;             const f32x2 E = {0.5f * (A.x + B.x), 0.5f * (A.y - B.y)}; const f32x2 Dm = {A.x - B.x, A.y + B.y}; const f32x2 O = {0.5f * Dm.y, -0.5f * Dm.x};
;             const float rev = (float)p * (1.f / 32768.f); const float c = __builtin_amdgcn_cosf(rev), sn = __builtin_amdgcn_sinf(rev);
;             const f32x2 WO = cmul((f32x2){c, -sn}, O);
;             const f32x2 Xk = E + WO; const f32x2 Xk2 = {E.x - WO.x, -(E.y - WO.y)};
;             const f32x2 Yk = cmul(Xk, (f32x2){hh.x, hh.y}), Yk2 = cmul(Xk2, (f32x2){hh.z, hh.w});
;             const f32x2 Ye = {0.5f * (Yk.x + Yk2.x), 0.5f * (Yk.y - Yk2.y)}; const f32x2 Dd = {Yk.x - Yk2.x, Yk.y + Yk2.y};
;             const f32x2 Yo = cmul((f32x2){0.5f * c, 0.5f * sn}, Dd);
;             X[i1] = (f32x2){Ye.x - Yo.y, Ye.y + Yo.x}; X[i2] = (f32x2){Ye.x + Yo.y, Yo.x - Ye.y};
.LBB0_182:
	s_or_b64 exec, exec, s[74:75]
	v_add_u32_e32 v5, 0x200, v5
	s_nop 0
	s_cmp_lg_u32 s2, 0
	s_cbranch_scc1 .Lhy174_last_2
	s_waitcnt vmcnt(3)
	v_mov_b32_e32 v0, v32
	v_mov_b32_e32 v1, v33
	v_mov_b32_e32 v2, v34
	v_mov_b32_e32 v3, v35
	v_add_co_u32_e32 v162, vcc, 0x6000, v6
	s_nop 1
	v_addc_co_u32_e32 v163, vcc, 0, v7, vcc
	global_load_dwordx4 v[32:35], v[162:163], off
	s_branch .Lhy174_join_2
.Lhy174_last_2:
	s_waitcnt vmcnt(0)
	v_mov_b32_e32 v0, v32
	v_mov_b32_e32 v1, v33
	v_mov_b32_e32 v2, v34
	v_mov_b32_e32 v3, v35
.Lhy174_join_2:
	v_cmp_ne_u32_e32 vcc, 0, v5
	s_and_saveexec_b64 s[0:1], vcc
	s_xor_b64 s[74:75], exec, s[0:1]
	s_cbranch_execz .LBB0_184
	v_add_u32_e32 v14, 0xfffffc00, v9
	v_ffbh_u32_e32 v10, v14
	v_lshrrev_b32_e64 v10, v10, s62
	v_add_u32_e32 v10, -1, v10
	v_xor_b32_e32 v12, v10, v14
	v_lshl_add_u32 v22, v12, 3, 0
	v_bfrev_b32_e32 v14, v14
	ds_read_b64 v[10:11], v8 offset:16384
	ds_read_b64 v[12:13], v22
	v_lshrrev_b32_e32 v14, 18, v14
	v_cvt_f32_u32_e32 v16, v14
	s_waitcnt lgkmcnt(0)
	v_pk_add_f32 v[14:15], v[10:11], v[12:13] neg_lo:[0,1] neg_hi:[0,1]
	v_pk_add_f32 v[10:11], v[10:11], v[12:13]
	v_mul_f32_e32 v13, 0x38000000, v16
	v_cos_f32_e32 v16, v13
	v_sin_f32_e32 v12, v13
	v_mul_f32_e32 v20, -0.5, v14
	v_mul_f32_e32 v18, 0.5, v11
	v_mov_b32_e32 v13, v16
	v_xor_b32_e32 v17, 0x80000000, v12
	v_pk_mul_f32 v[20:21], v[12:13], v[20:21] op_sel_hi:[1,0]
	v_pk_mov_b32 v[10:11], v[14:15], v[10:11] op_sel:[1,0]
	v_pk_fma_f32 v[18:19], v[16:17], v[18:19], v[20:21] op_sel_hi:[1,0,1]
	v_pk_mul_f32 v[14:15], v[10:11], 0.5 op_sel_hi:[1,0]
	v_pk_fma_f32 v[10:11], v[10:11], 0.5, v[18:19] op_sel:[0,0,1] op_sel_hi:[1,0,0] neg_lo:[0,0,1] neg_hi:[0,0,1]
	v_pk_add_f32 v[14:15], v[14:15], v[18:19] op_sel:[1,0] op_sel_hi:[0,1]
	v_xor_b32_e32 v20, 0x80000000, v15
	v_mov_b32_e32 v21, v14
	v_pk_mul_f32 v[20:21], v[0:1], v[20:21] op_sel:[1,0]
	v_xor_b32_e32 v19, 0x80000000, v10
	v_pk_fma_f32 v[0:1], v[0:1], v[14:15], v[20:21] op_sel_hi:[0,1,1]
	v_mov_b32_e32 v14, v3
	v_mov_b32_e32 v18, v11
	v_pk_mul_f32 v[10:11], v[14:15], v[10:11] op_sel_hi:[0,1]
	v_pk_fma_f32 v[2:3], v[2:3], v[18:19], v[10:11] op_sel_hi:[0,1,1]
	v_mov_b32_e32 v17, v12
	v_pk_add_f32 v[10:11], v[0:1], v[2:3] neg_lo:[0,1] neg_hi:[0,1]
	v_pk_add_f32 v[0:1], v[0:1], v[2:3]
	v_pk_mul_f32 v[2:3], v[16:17], 0.5 op_sel_hi:[1,0]
	s_nop 0
	v_xor_b32_e32 v12, 0x80000000, v3
	v_mov_b32_e32 v13, v2
	v_pk_mul_f32 v[12:13], v[12:13], v[0:1] op_sel:[0,1]
	s_nop 0
	v_pk_fma_f32 v[2:3], v[2:3], v[10:11], v[12:13] op_sel_hi:[1,0,1]
	v_mov_b32_e32 v10, v0
	v_pk_fma_f32 v[0:1], v[0:1], 0.5, v[2:3] op_sel:[0,0,1] op_sel_hi:[1,0,0] neg_lo:[0,0,1] neg_hi:[0,0,1]
	v_pk_fma_f32 v[12:13], v[10:11], 0.5, v[2:3] op_sel:[0,0,1] op_sel_hi:[1,0,0]
	s_nop 0
	v_mov_b32_e32 v1, v13
	ds_write_b64 v8, v[0:1] offset:16384
	v_pk_fma_f32 v[0:1], v[10:11], 0.5, v[2:3] op_sel_hi:[1,0,0] neg_lo:[1,0,0] neg_hi:[1,0,0]
	s_nop 0
	v_mov_b32_e32 v13, v1
	ds_write_b64 v22, v[12:13]

; __device__ __forceinline__ void pointwise_data(LAS f32x2* X, const f32x4* Hs, int tid) {
; #pragma unroll 4
;     for (int s = tid; s < 8192; s += NTHR) {
;         const f32x4 hh = Hs[s];
;         if (s == 0) {
;             const f32x2 A = X[0]; const float Y0 = (A.x + A.y) * hh.x, YM = (A.x - A.y) * hh.y; X[0] = (f32x2){0.5f * (Y0 + YM), 0.5f * (Y0 - YM)};
;             const f32x2 Cm = X[1]; const f32x2 Y = cmul((f32x2){Cm.x, -Cm.y}, (f32x2){hh.z, hh.w}); X[1] = (f32x2){Y.x, -Y.y};
;         } else {
;             const int i1 = 2 * s, i2 = i1 ^ ((1 << (31 - __clz(i1))) - 1); const int p = (int)(__brev((unsigned)i1) >> 18);
;             const f32x2 A = X[i1], B = X[i2];
;             const f32x2 E = {0.5f * (A.x + B.x), 0.5f * (A.y - B.y)}; const f32x2 Dm = {A.x - B.x, A.y + B.y}; const f32x2 O = {0.5f * Dm.y, -0.5f * Dm.x};
;             const float rev = (float)p * (1.f / 32768.f); const float c = __builtin_amdgcn_cosf(rev), sn = __builtin_amdgcn_sinf(rev);
;             const f32x2 WO = cmul((f32x2){c, -sn}, O);
;             const f32x2 Xk = E + WO; const f32x2 Xk2 = {E.x - WO.x, -(E.y - WO.y)};
;             const f32x2 Yk = cmul(Xk, (f32x2){hh.x, hh.y}), Yk2 = cmul(Xk2, (f32x2){hh.z, hh.w});
;             const f32x2 Ye = {0.5f * (Yk.x + Yk2.x), 0.5f * (Yk.y - Yk2.y)}; const f32x2 Dd = {Yk.x - Yk2.x, Yk.y + Yk2.y};
;             const f32x2 Yo = cmul((f32x2){0.5f * c, 0.5f * sn}, Dd);
;             X[i1] = (f32x2){Ye.x - Yo.y, Ye.y + Yo.x}; X[i2] = (f32x2){Ye.x + Yo.y, Yo.x - Ye.y};
.LBB0_186:
	s_or_b64 exec, exec, s[74:75]
	s_cmp_lg_u32 s2, 0
	s_cbranch_scc1 .Lhy174_last_3
	s_waitcnt vmcnt(3)
	v_mov_b32_e32 v0, v36
	v_mov_b32_e32 v1, v37
	v_mov_b32_e32 v2, v38
	v_mov_b32_e32 v3, v39
	v_add_co_u32_e32 v162, vcc, 0x8000, v6
	s_nop 1
	v_addc_co_u32_e32 v163, vcc, 0, v7, vcc
	global_load_dwordx4 v[36:39], v[162:163], off
	s_branch .Lhy174_join_3
.Lhy174_last_3:
	s_waitcnt vmcnt(0)
	v_mov_b32_e32 v0, v36
	v_mov_b32_e32 v1, v37
	v_mov_b32_e32 v2, v38
	v_mov_b32_e32 v3, v39
.Lhy174_join_3:
	v_cmp_ne_u32_e32 vcc, s83, v5
	s_and_saveexec_b64 s[0:1], vcc
	s_xor_b64 s[74:75], exec, s[0:1]
	s_cbranch_execz .LBB0_188
	v_ffbh_u32_e32 v5, v9
	v_lshrrev_b32_e64 v5, v5, s62
	v_add_u32_e32 v5, -1, v5
	v_xor_b32_e32 v5, v5, v9
	v_lshl_add_u32 v5, v5, 3, 0
	v_bfrev_b32_e32 v14, v9
	ds_read_b64 v[10:11], v8 offset:24576
	ds_read_b64 v[12:13], v5
	v_lshrrev_b32_e32 v14, 18, v14
	v_cvt_f32_u32_e32 v16, v14
	s_waitcnt lgkmcnt(0)
	v_pk_add_f32 v[14:15], v[10:11], v[12:13] neg_lo:[0,1] neg_hi:[0,1]
	v_pk_add_f32 v[10:11], v[10:11], v[12:13]
	v_mul_f32_e32 v13, 0x38000000, v16
	v_cos_f32_e32 v16, v13
	v_sin_f32_e32 v12, v13
	v_mul_f32_e32 v20, -0.5, v14
	v_mul_f32_e32 v18, 0.5, v11
	v_mov_b32_e32 v13, v16
	v_xor_b32_e32 v17, 0x80000000, v12
	v_pk_mul_f32 v[20:21], v[12:13], v[20:21] op_sel_hi:[1,0]
	v_pk_mov_b32 v[10:11], v[14:15], v[10:11] op_sel:[1,0]
	v_pk_fma_f32 v[18:19], v[16:17], v[18:19], v[20:21] op_sel_hi:[1,0,1]
	v_pk_mul_f32 v[14:15], v[10:11], 0.5 op_sel_hi:[1,0]
	v_pk_fma_f32 v[10:11], v[10:11], 0.5, v[18:19] op_sel:[0,0,1] op_sel_hi:[1,0,0] neg_lo:[0,0,1] neg_hi:[0,0,1]
	v_pk_add_f32 v[14:15], v[14:15], v[18:19] op_sel:[1,0] op_sel_hi:[0,1]
	v_xor_b32_e32 v20, 0x80000000, v15
	v_mov_b32_e32 v21, v14
	v_pk_mul_f32 v[20:21], v[0:1], v[20:21] op_sel:[1,0]
	v_xor_b32_e32 v19, 0x80000000, v10
	v_pk_fma_f32 v[0:1], v[0:1], v[14:15], v[20:21] op_sel_hi:[0,1,1]
	v_mov_b32_e32 v14, v3
	v_mov_b32_e32 v18, v11
	v_pk_mul_f32 v[10:11], v[14:15], v[10:11] op_sel_hi:[0,1]
	v_pk_fma_f32 v[2:3], v[2:3], v[18:19], v[10:11] op_sel_hi:[0,1,1]
	v_mov_b32_e32 v17, v12
	v_pk_add_f32 v[10:11], v[0:1], v[2:3] neg_lo:[0,1] neg_hi:[0,1]
	v_pk_add_f32 v[0:1], v[0:1], v[2:3]
	v_pk_mul_f32 v[2:3], v[16:17], 0.5 op_sel_hi:[1,0]
	s_nop 0
	v_xor_b32_e32 v12, 0x80000000, v3
	v_mov_b32_e32 v13, v2
	v_pk_mul_f32 v[12:13], v[12:13], v[0:1] op_sel:[0,1]
	s_nop 0
	v_pk_fma_f32 v[2:3], v[2:3], v[10:11], v[12:13] op_sel_hi:[1,0,1]
	v_mov_b32_e32 v10, v0
	v_pk_fma_f32 v[0:1], v[0:1], 0.5, v[2:3] op_sel:[0,0,1] op_sel_hi:[1,0,0] neg_lo:[0,0,1] neg_hi:[0,0,1]
	v_pk_fma_f32 v[12:13], v[10:11], 0.5, v[2:3] op_sel:[0,0,1] op_sel_hi:[1,0,0]
	s_nop 0
	v_mov_b32_e32 v1, v13
	ds_write_b64 v8, v[0:1] offset:24576
	v_pk_fma_f32 v[0:1], v[10:11], 0.5, v[2:3] op_sel_hi:[1,0,0] neg_lo:[1,0,0] neg_hi:[1,0,0]
	s_nop 0
	v_mov_b32_e32 v13, v1
	ds_write_b64 v5, v[12:13]
